# P10: the first 8 units of residual rows + the gate vector are requested inside the row-statistics exchange, before the counter poll
# speedup vs baseline: 1.0186x; 1.0012x over previous
; __global__ void __launch_bounds__(512, 2) mega_fwd(Args a) {
;     ...
;         const int ustep = (G == 256) ? 1 : G;
;         const int jx = vcu & 31;
;         const int u0 = (G == 256) ? (256 * (vcu >> 5) + (jx < 16 ? 7 * jx : 112 + 9 * (jx - 16))) : vcu;
;         const int ucnt = (G == 256) ? (bx < 128 ? 7 : 9) : (vcu < 2048 ? (2047 - vcu) / G + 1 : 0);
;         if (ucnt > 0) { const bf16_t* vp = Z + ((size_t)(u0 >> 3) * 128 + jt) * NZ + 1024 + (u0 & 7) * 64 + 16 * qd; r0 = *(const u32x4*)vp; r1 = *(const u32x4*)(vp + 8);
; #pragma unroll
;             for (int e4 = 0; e4 < 4; ++e4) { lgv[e4] = *(const f32x4*)(KA->gm_ln_g + (u0 & 7) * 64 + 16 * qd + 4 * e4); lbv[e4] = *(const f32x4*)(KA->gm_ln_b + (u0 & 7) * 64 + 16 * qd + 4 * e4); } }
.Lp3r_entry:
	s_and_b32 s10, s54, 31
	s_and_b32 s22, s10, 7
	s_lshr_b32 s11, s10, 3
	s_mul_i32 s12, s11, 7
	s_mul_i32 s13, s11, 9
	s_sub_u32 s13, s13, 4
	s_cmp_lt_u32 s11, 2
	s_cselect_b32 s12, s12, s13
	s_cselect_b32 s18, 7, 9
	s_and_b32 s39, s39, 0xffffff00
	s_lshr_b32 s39, s39, 3
	s_add_u32 s21, s39, s12
	s_mul_i32 s24, s21, 0x60000
	s_lshl_b32 s25, s22, 7
	s_add_u32 s24, s24, s25
	s_add_u32 s24, s24, 0x6000000
	s_add_u32 s26, s8, s24
	s_addc_u32 s27, s9, 0
	s_lshl_b32 s24, s21, 18
	s_add_u32 s24, s24, s25
	s_add_u32 s24, s24, 0x14a00000
	s_add_u32 s48, s8, s24
	s_addc_u32 s49, s9, 0
	s_lshl_b32 s24, s22, 15
	s_add_u32 s24, s24, 0x180000
	s_add_u32 s36, s8, s24
	s_addc_u32 s37, s9, 0
	s_lshl_b32 s24, s22, 9
	s_add_u32 s46, s16, s24
	s_addc_u32 s47, s17, 0
	s_lshl_b32 s24, s22, 8
	s_add_u32 s50, s40, s24
	s_addc_u32 s51, s41, 0
	s_add_u32 s52, s42, s24
	s_addc_u32 s53, s43, 0
	v_lshlrev_b32_e32 v109, 6, v104
	global_load_dwordx4 v[120:123], v114, s[36:37]
	global_load_dwordx4 v[124:127], v114, s[36:37] offset:32
	global_load_dwordx4 v[128:131], v114, s[36:37] offset:64
	global_load_dwordx4 v[132:135], v114, s[36:37] offset:96
	global_load_dwordx4 v[136:139], v114, s[36:37] offset:128
	global_load_dwordx4 v[140:143], v114, s[36:37] offset:160
	global_load_dwordx4 v[144:147], v114, s[36:37] offset:192
	global_load_dwordx4 v[148:151], v114, s[36:37] offset:224
	global_load_dword v32, v115, s[46:47]
	global_load_dwordx4 v[152:155], v109, s[50:51]
	global_load_dwordx4 v[156:159], v109, s[50:51] offset:16
	global_load_dwordx4 v[160:163], v109, s[50:51] offset:32
	global_load_dwordx4 v[164:167], v109, s[50:51] offset:48
	global_load_dwordx4 v[168:171], v109, s[52:53]
	global_load_dwordx4 v[172:175], v109, s[52:53] offset:16
	global_load_dwordx4 v[176:179], v109, s[52:53] offset:32
	global_load_dwordx4 v[180:183], v109, s[52:53] offset:48
	s_mov_b32 s45, 0
	global_load_dwordx4 v[16:19], v112, s[26:27]
	global_load_dwordx4 v[20:23], v112, s[26:27] offset:16
	global_load_dwordx2 v[24:25], v113, s[26:27]
	global_load_dwordx2 v[26:27], v113, s[26:27] offset:16
	global_load_dwordx2 v[28:29], v113, s[26:27] offset:32
	global_load_dwordx2 v[30:31], v113, s[26:27] offset:48
	s_add_u32 s26, s26, 0x60000
	s_addc_u32 s27, s27, 0
	s_cmp_lt_u32 s18, 2
	s_cbranch_scc1 .Lp3r_tail0
	global_load_dwordx4 v[40:43], v112, s[26:27]
	global_load_dwordx4 v[44:47], v112, s[26:27] offset:16
	global_load_dwordx2 v[48:49], v113, s[26:27]
	global_load_dwordx2 v[50:51], v113, s[26:27] offset:16
	global_load_dwordx2 v[52:53], v113, s[26:27] offset:32
	global_load_dwordx2 v[54:55], v113, s[26:27] offset:48
	s_add_u32 s26, s26, 0x60000
	s_addc_u32 s27, s27, 0

;     __device__ __forceinline__ void fused(f32x4 (&acc)[2][2][4][2], const Unit& u, int wr, int wc, int fr, int fq, PG8_LAS unsigned char* lds, int wid, int lane) const {
;     ...
;         for (int bj = 0; bj < 2; ++bj)
; #pragma unroll
;             for (int n = 0; n < 2; ++n) g[bj][n] = *(const f32x4*)(gv + col0 + bj * HALF + n * 16);
; #pragma unroll
;         for (int ai = 0; ai < 2; ++ai)
; #pragma unroll
;             for (int m = 0; m < 4; ++m) { const int r = ai * HALF + wr * 64 + m * 16 + fr; const float rs = S[r]; const size_t off = (size_t)(row_off + u.pm * BM + r) * DM + col0;
; #pragma unroll
;                 for (int bj = 0; bj < 2; ++bj)
; #pragma unroll
;                     for (int n = 0; n < 2; ++n) { const f32x4 bs = *(const f32x4*)(base + off + bj * HALF + n * 16); __builtin_nontemporal_store(bs + acc[ai][bj][m][n] * rs * g[bj][n], (f32x4*)(out + off + bj * HALF + n * 16)); }
;                 if (m & 1) asm volatile("" ::: "memory"); }
.LBB0_1113:
	s_or_b64 exec, exec, s[10:11]
	s_lshl_b32 s6, s50, 12
	s_add_i32 s6, s51, s6
	s_ashr_i32 s7, s6, 31
	s_lshl_b64 s[6:7], s[6:7], 2
	s_add_u32 s6, s14, s6
	s_addc_u32 s7, s15, s7
	s_lshl_b32 s9, s16, 5
	s_lshl_b32 s10, s24, 8
	v_lshrrev_b32_e32 v128, 2, v138
	s_or_b32 s9, s10, s9
	v_and_or_b32 v128, v128, 12, s9
	s_waitcnt lgkmcnt(0)
	v_ashrrev_i32_e32 v129, 31, v128
	v_lshlrev_b64 v[150:151], 2, v[128:129]
	s_lshl_b32 s8, s50, 14
	v_lshl_add_u64 v[128:129], s[6:7], 0, v[150:151]
	s_lshl_b32 s6, s53, 8
	s_add_i32 s6, s6, s8
	v_add_u32_e32 v152, s6, v157
	v_ashrrev_i32_e32 v153, 31, v152
	v_lshl_add_u64 v[140:141], v[128:129], 0, s[22:23]
	v_add_co_u32_e32 v128, vcc, s49, v128
	v_lshlrev_b64 v[132:133], 12, v[152:153]
	s_waitcnt lgkmcnt(0)
	s_barrier
	s_mov_b32 s7, 0
	s_lshl_b64 s[6:7], s[6:7], 12
	s_add_u32 s6, s12, s6
	s_addc_u32 s7, s13, s7
	v_and_b32_e32 v136, 8, v157
	v_sub_u32_e32 v157, v157, v136
	v_lshlrev_b32_e32 v137, 3, v136
	v_lshl_add_u32 v144, v157, 2, 0
	v_add_u32_e32 v144, 0x1000, v144
	v_lshl_add_u32 v157, v157, 12, v150
	v_add_u32_e32 v157, v157, v137
	ds_read2_b32 v[228:229], v144 offset0:0 offset1:8
	ds_read2_b32 v[230:231], v144 offset0:16 offset1:24
	ds_read2_b32 v[232:233], v144 offset0:32 offset1:40
	ds_read2_b32 v[234:235], v144 offset0:48 offset1:56
	ds_read2_b32 v[236:237], v144 offset0:128 offset1:136
	ds_read2_b32 v[238:239], v144 offset0:144 offset1:152
	ds_read2_b32 v[240:241], v144 offset0:160 offset1:168
	ds_read2_b32 v[242:243], v144 offset0:176 offset1:184
	s_waitcnt lgkmcnt(0)
	v_mov_b32_e32 v190, v124
	v_mov_b32_e32 v191, v125
	v_mov_b32_e32 v192, v126
	v_mov_b32_e32 v193, v127
	v_mov_b32_dpp v124, v120 row_ror:8 row_mask:0xf bank_mask:0xc
	v_mov_b32_dpp v125, v121 row_ror:8 row_mask:0xf bank_mask:0xc
	v_mov_b32_dpp v126, v122 row_ror:8 row_mask:0xf bank_mask:0xc
	v_mov_b32_dpp v127, v123 row_ror:8 row_mask:0xf bank_mask:0xc
	v_mov_b32_dpp v120, v190 row_ror:8 row_mask:0xf bank_mask:0x3
	v_mov_b32_dpp v121, v191 row_ror:8 row_mask:0xf bank_mask:0x3
	v_mov_b32_dpp v122, v192 row_ror:8 row_mask:0xf bank_mask:0x3
	v_mov_b32_dpp v123, v193 row_ror:8 row_mask:0xf bank_mask:0x3
	s_waitcnt vmcnt(14)
	v_mul_f32_e32 v124, v124, v228
	v_mul_f32_e32 v125, v125, v228
	v_mul_f32_e32 v126, v126, v228
	v_mul_f32_e32 v127, v127, v228
	v_mul_f32_e32 v120, v120, v229
	v_mul_f32_e32 v121, v121, v229
	v_mul_f32_e32 v122, v122, v229
	v_mul_f32_e32 v123, v123, v229
	v_fma_f32 v124, v124, v244, v158
	v_fma_f32 v125, v125, v245, v159
	v_fma_f32 v126, v126, v246, v160
	v_fma_f32 v127, v127, v247, v161
	v_fma_f32 v120, v120, v244, v162
	v_fma_f32 v121, v121, v245, v163
	v_fma_f32 v122, v122, v246, v164
	v_fma_f32 v123, v123, v247, v165
	v_mov_b32_e32 v252, v157
	v_add_u32_e32 v253, 0x8000, v157
	global_store_dwordx4 v252, v[124:127], s[6:7] nt
	global_store_dwordx4 v253, v[120:123], s[6:7] nt
	v_add_u32_e32 v252, 0x80000, v157
	v_add_u32_e32 v253, 0x88000, v157
	global_load_dwordx4 v[158:161], v252, s[6:7] nt
	global_load_dwordx4 v[162:165], v253, s[6:7] nt
	v_mov_b32_e32 v190, v108
	v_mov_b32_e32 v191, v109
	v_mov_b32_e32 v192, v110
	v_mov_b32_e32 v193, v111
	v_mov_b32_dpp v108, v104 row_ror:8 row_mask:0xf bank_mask:0xc
	v_mov_b32_dpp v109, v105 row_ror:8 row_mask:0xf bank_mask:0xc
	v_mov_b32_dpp v110, v106 row_ror:8 row_mask:0xf bank_mask:0xc
	v_mov_b32_dpp v111, v107 row_ror:8 row_mask:0xf bank_mask:0xc
	v_mov_b32_dpp v104, v190 row_ror:8 row_mask:0xf bank_mask:0x3
	v_mov_b32_dpp v105, v191 row_ror:8 row_mask:0xf bank_mask:0x3
	v_mov_b32_dpp v106, v192 row_ror:8 row_mask:0xf bank_mask:0x3
	v_mov_b32_dpp v107, v193 row_ror:8 row_mask:0xf bank_mask:0x3
	s_waitcnt vmcnt(16)
	v_mul_f32_e32 v108, v108, v228
	v_mul_f32_e32 v109, v109, v228
	v_mul_f32_e32 v110, v110, v228
	v_mul_f32_e32 v111, v111, v228
	v_mul_f32_e32 v104, v104, v229
	v_mul_f32_e32 v105, v105, v229
	v_mul_f32_e32 v106, v106, v229
	v_mul_f32_e32 v107, v107, v229
	v_fma_f32 v108, v108, v248, v166
	v_fma_f32 v109, v109, v249, v167
	v_fma_f32 v110, v110, v250, v168
	v_fma_f32 v111, v111, v251, v169
	v_fma_f32 v104, v104, v248, v170
	v_fma_f32 v105, v105, v249, v171
	v_fma_f32 v106, v106, v250, v172
	v_fma_f32 v107, v107, v251, v173
	v_mov_b32_e32 v252, v157
	v_add_u32_e32 v253, 0x8000, v157
	global_store_dwordx4 v252, v[108:111], s[6:7] offset:512 nt
	global_store_dwordx4 v253, v[104:107], s[6:7] offset:512 nt
	v_add_u32_e32 v252, 0x80000, v157
	v_add_u32_e32 v253, 0x88000, v157
	global_load_dwordx4 v[166:169], v252, s[6:7] offset:512 nt
	global_load_dwordx4 v[170:173], v253, s[6:7] offset:512 nt
	v_mov_b32_e32 v190, v116
	v_mov_b32_e32 v191, v117
	v_mov_b32_e32 v192, v118
	v_mov_b32_e32 v193, v119
	v_mov_b32_dpp v116, v112 row_ror:8 row_mask:0xf bank_mask:0xc
	v_mov_b32_dpp v117, v113 row_ror:8 row_mask:0xf bank_mask:0xc
	v_mov_b32_dpp v118, v114 row_ror:8 row_mask:0xf bank_mask:0xc
	v_mov_b32_dpp v119, v115 row_ror:8 row_mask:0xf bank_mask:0xc
	v_mov_b32_dpp v112, v190 row_ror:8 row_mask:0xf bank_mask:0x3
	v_mov_b32_dpp v113, v191 row_ror:8 row_mask:0xf bank_mask:0x3
	v_mov_b32_dpp v114, v192 row_ror:8 row_mask:0xf bank_mask:0x3
	v_mov_b32_dpp v115, v193 row_ror:8 row_mask:0xf bank_mask:0x3
	s_waitcnt vmcnt(18)
;     __device__ __forceinline__ void fused(f32x4 (&acc)[2][2][4][2], const Unit& u, int wr, int wc, int fr, int fq, PG8_LAS unsigned char* lds, int wid, int lane) const {
;     ...
; #pragma unroll
;         for (int ai = 0; ai < 2; ++ai)
; #pragma unroll
;             for (int m = 0; m < 4; ++m) { const int r = ai * HALF + wr * 64 + m * 16 + fr; const float rs = S[r]; const size_t off = (size_t)(row_off + u.pm * BM + r) * DM + col0;
; #pragma unroll
;                 for (int bj = 0; bj < 2; ++bj)
; #pragma unroll
;                     for (int n = 0; n < 2; ++n) { const f32x4 bs = *(const f32x4*)(base + off + bj * HALF + n * 16); __builtin_nontemporal_store(bs + acc[ai][bj][m][n] * rs * g[bj][n], (f32x4*)(out + off + bj * HALF + n * 16)); }
;                 if (m & 1) asm volatile("" ::: "memory"); }
	v_mul_f32_e32 v116, v116, v230
	v_mul_f32_e32 v117, v117, v230
	v_mul_f32_e32 v118, v118, v230
	v_mul_f32_e32 v119, v119, v230
	v_mul_f32_e32 v112, v112, v231
	v_mul_f32_e32 v113, v113, v231
	v_mul_f32_e32 v114, v114, v231
	v_mul_f32_e32 v115, v115, v231
	v_fma_f32 v116, v116, v244, v174
	v_fma_f32 v117, v117, v245, v175
	v_fma_f32 v118, v118, v246, v176
	v_fma_f32 v119, v119, v247, v177
	v_fma_f32 v112, v112, v244, v178
	v_fma_f32 v113, v113, v245, v179
	v_fma_f32 v114, v114, v246, v180
	v_fma_f32 v115, v115, v247, v181
	v_add_u32_e32 v252, 0x10000, v157
	v_add_u32_e32 v253, 0x18000, v157
	global_store_dwordx4 v252, v[116:119], s[6:7] nt
	global_store_dwordx4 v253, v[112:115], s[6:7] nt
	v_add_u32_e32 v252, 0x90000, v157
	v_add_u32_e32 v253, 0x98000, v157
	global_load_dwordx4 v[174:177], v252, s[6:7] nt
	global_load_dwordx4 v[178:181], v253, s[6:7] nt
	v_mov_b32_e32 v190, v100
	v_mov_b32_e32 v191, v101
	v_mov_b32_e32 v192, v102
	v_mov_b32_e32 v193, v103
	v_mov_b32_dpp v100, v96 row_ror:8 row_mask:0xf bank_mask:0xc
	v_mov_b32_dpp v101, v97 row_ror:8 row_mask:0xf bank_mask:0xc
	v_mov_b32_dpp v102, v98 row_ror:8 row_mask:0xf bank_mask:0xc
	v_mov_b32_dpp v103, v99 row_ror:8 row_mask:0xf bank_mask:0xc
	v_mov_b32_dpp v96, v190 row_ror:8 row_mask:0xf bank_mask:0x3
	v_mov_b32_dpp v97, v191 row_ror:8 row_mask:0xf bank_mask:0x3
	v_mov_b32_dpp v98, v192 row_ror:8 row_mask:0xf bank_mask:0x3
	v_mov_b32_dpp v99, v193 row_ror:8 row_mask:0xf bank_mask:0x3
	s_waitcnt vmcnt(20)
	v_mul_f32_e32 v100, v100, v230
	v_mul_f32_e32 v101, v101, v230
	v_mul_f32_e32 v102, v102, v230
	v_mul_f32_e32 v103, v103, v230
	v_mul_f32_e32 v96, v96, v231
	v_mul_f32_e32 v97, v97, v231
	v_mul_f32_e32 v98, v98, v231
	v_mul_f32_e32 v99, v99, v231
	v_fma_f32 v100, v100, v248, v182
	v_fma_f32 v101, v101, v249, v183
	v_fma_f32 v102, v102, v250, v184
	v_fma_f32 v103, v103, v251, v185
	v_fma_f32 v96, v96, v248, v186
	v_fma_f32 v97, v97, v249, v187
	v_fma_f32 v98, v98, v250, v188
	v_fma_f32 v99, v99, v251, v189
	v_add_u32_e32 v252, 0x10000, v157
	v_add_u32_e32 v253, 0x18000, v157
	global_store_dwordx4 v252, v[100:103], s[6:7] offset:512 nt
	global_store_dwordx4 v253, v[96:99], s[6:7] offset:512 nt
	v_add_u32_e32 v252, 0x90000, v157
	v_add_u32_e32 v253, 0x98000, v157
	global_load_dwordx4 v[182:185], v252, s[6:7] offset:512 nt
	global_load_dwordx4 v[186:189], v253, s[6:7] offset:512 nt
	v_mov_b32_e32 v190, v92
	v_mov_b32_e32 v191, v93
	v_mov_b32_e32 v192, v94
	v_mov_b32_e32 v193, v95
	v_mov_b32_dpp v92, v88 row_ror:8 row_mask:0xf bank_mask:0xc
	v_mov_b32_dpp v93, v89 row_ror:8 row_mask:0xf bank_mask:0xc
	v_mov_b32_dpp v94, v90 row_ror:8 row_mask:0xf bank_mask:0xc
	v_mov_b32_dpp v95, v91 row_ror:8 row_mask:0xf bank_mask:0xc
	v_mov_b32_dpp v88, v190 row_ror:8 row_mask:0xf bank_mask:0x3
	v_mov_b32_dpp v89, v191 row_ror:8 row_mask:0xf bank_mask:0x3
	v_mov_b32_dpp v90, v192 row_ror:8 row_mask:0xf bank_mask:0x3
	v_mov_b32_dpp v91, v193 row_ror:8 row_mask:0xf bank_mask:0x3
	s_waitcnt vmcnt(22)
	v_mul_f32_e32 v92, v92, v232
	v_mul_f32_e32 v93, v93, v232
	v_mul_f32_e32 v94, v94, v232
	v_mul_f32_e32 v95, v95, v232
	v_mul_f32_e32 v88, v88, v233
	v_mul_f32_e32 v89, v89, v233
	v_mul_f32_e32 v90, v90, v233
	v_mul_f32_e32 v91, v91, v233
	v_fma_f32 v92, v92, v244, v196
	v_fma_f32 v93, v93, v245, v197
	v_fma_f32 v94, v94, v246, v198
	v_fma_f32 v95, v95, v247, v199
	v_fma_f32 v88, v88, v244, v200
	v_fma_f32 v89, v89, v245, v201
	v_fma_f32 v90, v90, v246, v202
	v_fma_f32 v91, v91, v247, v203
	v_add_u32_e32 v252, 0x20000, v157
	v_add_u32_e32 v253, 0x28000, v157
	global_store_dwordx4 v252, v[92:95], s[6:7] nt
	global_store_dwordx4 v253, v[88:91], s[6:7] nt
	v_add_u32_e32 v252, 0xa0000, v157
	v_add_u32_e32 v253, 0xa8000, v157
	global_load_dwordx4 v[196:199], v252, s[6:7] nt
	global_load_dwordx4 v[200:203], v253, s[6:7] nt
	v_mov_b32_e32 v190, v76
	v_mov_b32_e32 v191, v77
	v_mov_b32_e32 v192, v78
	v_mov_b32_e32 v193, v79
	v_mov_b32_dpp v76, v72 row_ror:8 row_mask:0xf bank_mask:0xc
	v_mov_b32_dpp v77, v73 row_ror:8 row_mask:0xf bank_mask:0xc
	v_mov_b32_dpp v78, v74 row_ror:8 row_mask:0xf bank_mask:0xc
	v_mov_b32_dpp v79, v75 row_ror:8 row_mask:0xf bank_mask:0xc
	v_mov_b32_dpp v72, v190 row_ror:8 row_mask:0xf bank_mask:0x3
	v_mov_b32_dpp v73, v191 row_ror:8 row_mask:0xf bank_mask:0x3
	v_mov_b32_dpp v74, v192 row_ror:8 row_mask:0xf bank_mask:0x3
	v_mov_b32_dpp v75, v193 row_ror:8 row_mask:0xf bank_mask:0x3
	s_waitcnt vmcnt(24)
	v_mul_f32_e32 v76, v76, v232
	v_mul_f32_e32 v77, v77, v232
	v_mul_f32_e32 v78, v78, v232
	v_mul_f32_e32 v79, v79, v232
	v_mul_f32_e32 v72, v72, v233
	v_mul_f32_e32 v73, v73, v233
	v_mul_f32_e32 v74, v74, v233
	v_mul_f32_e32 v75, v75, v233
	v_fma_f32 v76, v76, v248, v204
	v_fma_f32 v77, v77, v249, v205
	v_fma_f32 v78, v78, v250, v206
	v_fma_f32 v79, v79, v251, v207
	v_fma_f32 v72, v72, v248, v208
	v_fma_f32 v73, v73, v249, v209
	v_fma_f32 v74, v74, v250, v210
	v_fma_f32 v75, v75, v251, v211
	v_add_u32_e32 v252, 0x20000, v157
	v_add_u32_e32 v253, 0x28000, v157
	global_store_dwordx4 v252, v[76:79], s[6:7] offset:512 nt
	global_store_dwordx4 v253, v[72:75], s[6:7] offset:512 nt
	v_add_u32_e32 v252, 0xa0000, v157
	v_add_u32_e32 v253, 0xa8000, v157
	global_load_dwordx4 v[204:207], v252, s[6:7] offset:512 nt
	global_load_dwordx4 v[208:211], v253, s[6:7] offset:512 nt
	v_mov_b32_e32 v190, v84
	v_mov_b32_e32 v191, v85
	v_mov_b32_e32 v192, v86
	v_mov_b32_e32 v193, v87
	v_mov_b32_dpp v84, v80 row_ror:8 row_mask:0xf bank_mask:0xc
	v_mov_b32_dpp v85, v81 row_ror:8 row_mask:0xf bank_mask:0xc
	v_mov_b32_dpp v86, v82 row_ror:8 row_mask:0xf bank_mask:0xc
	v_mov_b32_dpp v87, v83 row_ror:8 row_mask:0xf bank_mask:0xc
	v_mov_b32_dpp v80, v190 row_ror:8 row_mask:0xf bank_mask:0x3
	v_mov_b32_dpp v81, v191 row_ror:8 row_mask:0xf bank_mask:0x3
	v_mov_b32_dpp v82, v192 row_ror:8 row_mask:0xf bank_mask:0x3
	v_mov_b32_dpp v83, v193 row_ror:8 row_mask:0xf bank_mask:0x3
	s_waitcnt vmcnt(26)
;     __device__ __forceinline__ void fused(f32x4 (&acc)[2][2][4][2], const Unit& u, int wr, int wc, int fr, int fq, PG8_LAS unsigned char* lds, int wid, int lane) const {
;     ...
; #pragma unroll
;         for (int ai = 0; ai < 2; ++ai)
; #pragma unroll
;             for (int m = 0; m < 4; ++m) { const int r = ai * HALF + wr * 64 + m * 16 + fr; const float rs = S[r]; const size_t off = (size_t)(row_off + u.pm * BM + r) * DM + col0;
; #pragma unroll
;                 for (int bj = 0; bj < 2; ++bj)
; #pragma unroll
;                     for (int n = 0; n < 2; ++n) { const f32x4 bs = *(const f32x4*)(base + off + bj * HALF + n * 16); __builtin_nontemporal_store(bs + acc[ai][bj][m][n] * rs * g[bj][n], (f32x4*)(out + off + bj * HALF + n * 16)); }
;                 if (m & 1) asm volatile("" ::: "memory"); }
	v_mul_f32_e32 v84, v84, v234
	v_mul_f32_e32 v85, v85, v234
	v_mul_f32_e32 v86, v86, v234
	v_mul_f32_e32 v87, v87, v234
	v_mul_f32_e32 v80, v80, v235
	v_mul_f32_e32 v81, v81, v235
	v_mul_f32_e32 v82, v82, v235
	v_mul_f32_e32 v83, v83, v235
	v_fma_f32 v84, v84, v244, v212
	v_fma_f32 v85, v85, v245, v213
	v_fma_f32 v86, v86, v246, v214
	v_fma_f32 v87, v87, v247, v215
	v_fma_f32 v80, v80, v244, v216
	v_fma_f32 v81, v81, v245, v217
	v_fma_f32 v82, v82, v246, v218
	v_fma_f32 v83, v83, v247, v219
	v_add_u32_e32 v252, 0x30000, v157
	v_add_u32_e32 v253, 0x38000, v157
	global_store_dwordx4 v252, v[84:87], s[6:7] nt
	global_store_dwordx4 v253, v[80:83], s[6:7] nt
	v_add_u32_e32 v252, 0xb0000, v157
	v_add_u32_e32 v253, 0xb8000, v157
	global_load_dwordx4 v[212:215], v252, s[6:7] nt
	global_load_dwordx4 v[216:219], v253, s[6:7] nt
	v_mov_b32_e32 v190, v68
	v_mov_b32_e32 v191, v69
	v_mov_b32_e32 v192, v70
	v_mov_b32_e32 v193, v71
	v_mov_b32_dpp v68, v64 row_ror:8 row_mask:0xf bank_mask:0xc
	v_mov_b32_dpp v69, v65 row_ror:8 row_mask:0xf bank_mask:0xc
	v_mov_b32_dpp v70, v66 row_ror:8 row_mask:0xf bank_mask:0xc
	v_mov_b32_dpp v71, v67 row_ror:8 row_mask:0xf bank_mask:0xc
	v_mov_b32_dpp v64, v190 row_ror:8 row_mask:0xf bank_mask:0x3
	v_mov_b32_dpp v65, v191 row_ror:8 row_mask:0xf bank_mask:0x3
	v_mov_b32_dpp v66, v192 row_ror:8 row_mask:0xf bank_mask:0x3
	v_mov_b32_dpp v67, v193 row_ror:8 row_mask:0xf bank_mask:0x3
	s_waitcnt vmcnt(28)
	v_mul_f32_e32 v68, v68, v234
	v_mul_f32_e32 v69, v69, v234
	v_mul_f32_e32 v70, v70, v234
	v_mul_f32_e32 v71, v71, v234
	v_mul_f32_e32 v64, v64, v235
	v_mul_f32_e32 v65, v65, v235
	v_mul_f32_e32 v66, v66, v235
	v_mul_f32_e32 v67, v67, v235
	v_fma_f32 v68, v68, v248, v220
	v_fma_f32 v69, v69, v249, v221
	v_fma_f32 v70, v70, v250, v222
	v_fma_f32 v71, v71, v251, v223
	v_fma_f32 v64, v64, v248, v224
	v_fma_f32 v65, v65, v249, v225
	v_fma_f32 v66, v66, v250, v226
	v_fma_f32 v67, v67, v251, v227
	v_add_u32_e32 v252, 0x30000, v157
	v_add_u32_e32 v253, 0x38000, v157
	global_store_dwordx4 v252, v[68:71], s[6:7] offset:512 nt
	global_store_dwordx4 v253, v[64:67], s[6:7] offset:512 nt
	v_add_u32_e32 v252, 0xb0000, v157
	v_add_u32_e32 v253, 0xb8000, v157
	global_load_dwordx4 v[220:223], v252, s[6:7] offset:512 nt
	global_load_dwordx4 v[224:227], v253, s[6:7] offset:512 nt
	v_mov_b32_e32 v190, v60
	v_mov_b32_e32 v191, v61
	v_mov_b32_e32 v192, v62
	v_mov_b32_e32 v193, v63
	v_mov_b32_dpp v60, v56 row_ror:8 row_mask:0xf bank_mask:0xc
	v_mov_b32_dpp v61, v57 row_ror:8 row_mask:0xf bank_mask:0xc
	v_mov_b32_dpp v62, v58 row_ror:8 row_mask:0xf bank_mask:0xc
	v_mov_b32_dpp v63, v59 row_ror:8 row_mask:0xf bank_mask:0xc
	v_mov_b32_dpp v56, v190 row_ror:8 row_mask:0xf bank_mask:0x3
	v_mov_b32_dpp v57, v191 row_ror:8 row_mask:0xf bank_mask:0x3
	v_mov_b32_dpp v58, v192 row_ror:8 row_mask:0xf bank_mask:0x3
	v_mov_b32_dpp v59, v193 row_ror:8 row_mask:0xf bank_mask:0x3
	s_waitcnt vmcnt(28)
	v_mul_f32_e32 v60, v60, v236
	v_mul_f32_e32 v61, v61, v236
	v_mul_f32_e32 v62, v62, v236
	v_mul_f32_e32 v63, v63, v236
	v_mul_f32_e32 v56, v56, v237
	v_mul_f32_e32 v57, v57, v237
	v_mul_f32_e32 v58, v58, v237
	v_mul_f32_e32 v59, v59, v237
	v_fma_f32 v60, v60, v244, v158
	v_fma_f32 v61, v61, v245, v159
	v_fma_f32 v62, v62, v246, v160
	v_fma_f32 v63, v63, v247, v161
	v_fma_f32 v56, v56, v244, v162
	v_fma_f32 v57, v57, v245, v163
	v_fma_f32 v58, v58, v246, v164
	v_fma_f32 v59, v59, v247, v165
	v_add_u32_e32 v252, 0x80000, v157
	v_add_u32_e32 v253, 0x88000, v157
	global_store_dwordx4 v252, v[60:63], s[6:7] nt
	global_store_dwordx4 v253, v[56:59], s[6:7] nt
	v_mov_b32_e32 v190, v44
	v_mov_b32_e32 v191, v45
	v_mov_b32_e32 v192, v46
	v_mov_b32_e32 v193, v47
	v_mov_b32_dpp v44, v40 row_ror:8 row_mask:0xf bank_mask:0xc
	v_mov_b32_dpp v45, v41 row_ror:8 row_mask:0xf bank_mask:0xc
	v_mov_b32_dpp v46, v42 row_ror:8 row_mask:0xf bank_mask:0xc
	v_mov_b32_dpp v47, v43 row_ror:8 row_mask:0xf bank_mask:0xc
	v_mov_b32_dpp v40, v190 row_ror:8 row_mask:0xf bank_mask:0x3
	v_mov_b32_dpp v41, v191 row_ror:8 row_mask:0xf bank_mask:0x3
	v_mov_b32_dpp v42, v192 row_ror:8 row_mask:0xf bank_mask:0x3
	v_mov_b32_dpp v43, v193 row_ror:8 row_mask:0xf bank_mask:0x3
	s_waitcnt vmcnt(26)
	v_mul_f32_e32 v44, v44, v236
	v_mul_f32_e32 v45, v45, v236
	v_mul_f32_e32 v46, v46, v236
	v_mul_f32_e32 v47, v47, v236
	v_mul_f32_e32 v40, v40, v237
	v_mul_f32_e32 v41, v41, v237
	v_mul_f32_e32 v42, v42, v237
	v_mul_f32_e32 v43, v43, v237
	v_fma_f32 v44, v44, v248, v166
	v_fma_f32 v45, v45, v249, v167
	v_fma_f32 v46, v46, v250, v168
	v_fma_f32 v47, v47, v251, v169
	v_fma_f32 v40, v40, v248, v170
	v_fma_f32 v41, v41, v249, v171
	v_fma_f32 v42, v42, v250, v172
	v_fma_f32 v43, v43, v251, v173
	v_add_u32_e32 v252, 0x80000, v157
	v_add_u32_e32 v253, 0x88000, v157
	global_store_dwordx4 v252, v[44:47], s[6:7] offset:512 nt
	global_store_dwordx4 v253, v[40:43], s[6:7] offset:512 nt
	v_mov_b32_e32 v190, v52
	v_mov_b32_e32 v191, v53
	v_mov_b32_e32 v192, v54
	v_mov_b32_e32 v193, v55
	v_mov_b32_dpp v52, v48 row_ror:8 row_mask:0xf bank_mask:0xc
	v_mov_b32_dpp v53, v49 row_ror:8 row_mask:0xf bank_mask:0xc
	v_mov_b32_dpp v54, v50 row_ror:8 row_mask:0xf bank_mask:0xc
	v_mov_b32_dpp v55, v51 row_ror:8 row_mask:0xf bank_mask:0xc
	v_mov_b32_dpp v48, v190 row_ror:8 row_mask:0xf bank_mask:0x3
	v_mov_b32_dpp v49, v191 row_ror:8 row_mask:0xf bank_mask:0x3
	v_mov_b32_dpp v50, v192 row_ror:8 row_mask:0xf bank_mask:0x3
	v_mov_b32_dpp v51, v193 row_ror:8 row_mask:0xf bank_mask:0x3
	s_waitcnt vmcnt(24)
;     __device__ __forceinline__ void fused(f32x4 (&acc)[2][2][4][2], const Unit& u, int wr, int wc, int fr, int fq, PG8_LAS unsigned char* lds, int wid, int lane) const {
;     ...
; #pragma unroll
;         for (int ai = 0; ai < 2; ++ai)
; #pragma unroll
;             for (int m = 0; m < 4; ++m) { const int r = ai * HALF + wr * 64 + m * 16 + fr; const float rs = S[r]; const size_t off = (size_t)(row_off + u.pm * BM + r) * DM + col0;
; #pragma unroll
;                 for (int bj = 0; bj < 2; ++bj)
; #pragma unroll
;                     for (int n = 0; n < 2; ++n) { const f32x4 bs = *(const f32x4*)(base + off + bj * HALF + n * 16); __builtin_nontemporal_store(bs + acc[ai][bj][m][n] * rs * g[bj][n], (f32x4*)(out + off + bj * HALF + n * 16)); }
;                 if (m & 1) asm volatile("" ::: "memory"); }
	v_mul_f32_e32 v52, v52, v238
	v_mul_f32_e32 v53, v53, v238
	v_mul_f32_e32 v54, v54, v238
	v_mul_f32_e32 v55, v55, v238
	v_mul_f32_e32 v48, v48, v239
	v_mul_f32_e32 v49, v49, v239
	v_mul_f32_e32 v50, v50, v239
	v_mul_f32_e32 v51, v51, v239
	v_fma_f32 v52, v52, v244, v174
	v_fma_f32 v53, v53, v245, v175
	v_fma_f32 v54, v54, v246, v176
	v_fma_f32 v55, v55, v247, v177
	v_fma_f32 v48, v48, v244, v178
	v_fma_f32 v49, v49, v245, v179
	v_fma_f32 v50, v50, v246, v180
	v_fma_f32 v51, v51, v247, v181
	v_add_u32_e32 v252, 0x90000, v157
	v_add_u32_e32 v253, 0x98000, v157
	global_store_dwordx4 v252, v[52:55], s[6:7] nt
	global_store_dwordx4 v253, v[48:51], s[6:7] nt
	v_mov_b32_e32 v190, v36
	v_mov_b32_e32 v191, v37
	v_mov_b32_e32 v192, v38
	v_mov_b32_e32 v193, v39
	v_mov_b32_dpp v36, v32 row_ror:8 row_mask:0xf bank_mask:0xc
	v_mov_b32_dpp v37, v33 row_ror:8 row_mask:0xf bank_mask:0xc
	v_mov_b32_dpp v38, v34 row_ror:8 row_mask:0xf bank_mask:0xc
	v_mov_b32_dpp v39, v35 row_ror:8 row_mask:0xf bank_mask:0xc
	v_mov_b32_dpp v32, v190 row_ror:8 row_mask:0xf bank_mask:0x3
	v_mov_b32_dpp v33, v191 row_ror:8 row_mask:0xf bank_mask:0x3
	v_mov_b32_dpp v34, v192 row_ror:8 row_mask:0xf bank_mask:0x3
	v_mov_b32_dpp v35, v193 row_ror:8 row_mask:0xf bank_mask:0x3
	s_waitcnt vmcnt(22)
	v_mul_f32_e32 v36, v36, v238
	v_mul_f32_e32 v37, v37, v238
	v_mul_f32_e32 v38, v38, v238
	v_mul_f32_e32 v39, v39, v238
	v_mul_f32_e32 v32, v32, v239
	v_mul_f32_e32 v33, v33, v239
	v_mul_f32_e32 v34, v34, v239
	v_mul_f32_e32 v35, v35, v239
	v_fma_f32 v36, v36, v248, v182
	v_fma_f32 v37, v37, v249, v183
	v_fma_f32 v38, v38, v250, v184
	v_fma_f32 v39, v39, v251, v185
	v_fma_f32 v32, v32, v248, v186
	v_fma_f32 v33, v33, v249, v187
	v_fma_f32 v34, v34, v250, v188
	v_fma_f32 v35, v35, v251, v189
	v_add_u32_e32 v252, 0x90000, v157
	v_add_u32_e32 v253, 0x98000, v157
	global_store_dwordx4 v252, v[36:39], s[6:7] offset:512 nt
	global_store_dwordx4 v253, v[32:35], s[6:7] offset:512 nt
	v_mov_b32_e32 v190, v28
	v_mov_b32_e32 v191, v29
	v_mov_b32_e32 v192, v30
	v_mov_b32_e32 v193, v31
	v_mov_b32_dpp v28, v24 row_ror:8 row_mask:0xf bank_mask:0xc
	v_mov_b32_dpp v29, v25 row_ror:8 row_mask:0xf bank_mask:0xc
	v_mov_b32_dpp v30, v26 row_ror:8 row_mask:0xf bank_mask:0xc
	v_mov_b32_dpp v31, v27 row_ror:8 row_mask:0xf bank_mask:0xc
	v_mov_b32_dpp v24, v190 row_ror:8 row_mask:0xf bank_mask:0x3
	v_mov_b32_dpp v25, v191 row_ror:8 row_mask:0xf bank_mask:0x3
	v_mov_b32_dpp v26, v192 row_ror:8 row_mask:0xf bank_mask:0x3
	v_mov_b32_dpp v27, v193 row_ror:8 row_mask:0xf bank_mask:0x3
	s_waitcnt vmcnt(20)
	v_mul_f32_e32 v28, v28, v240
	v_mul_f32_e32 v29, v29, v240
	v_mul_f32_e32 v30, v30, v240
	v_mul_f32_e32 v31, v31, v240
	v_mul_f32_e32 v24, v24, v241
	v_mul_f32_e32 v25, v25, v241
	v_mul_f32_e32 v26, v26, v241
	v_mul_f32_e32 v27, v27, v241
	v_fma_f32 v28, v28, v244, v196
	v_fma_f32 v29, v29, v245, v197
	v_fma_f32 v30, v30, v246, v198
	v_fma_f32 v31, v31, v247, v199
	v_fma_f32 v24, v24, v244, v200
	v_fma_f32 v25, v25, v245, v201
	v_fma_f32 v26, v26, v246, v202
	v_fma_f32 v27, v27, v247, v203
	v_add_u32_e32 v252, 0xa0000, v157
	v_add_u32_e32 v253, 0xa8000, v157
	global_store_dwordx4 v252, v[28:31], s[6:7] nt
	global_store_dwordx4 v253, v[24:27], s[6:7] nt
	v_mov_b32_e32 v190, v12
	v_mov_b32_e32 v191, v13
	v_mov_b32_e32 v192, v14
	v_mov_b32_e32 v193, v15
	v_mov_b32_dpp v12, v8 row_ror:8 row_mask:0xf bank_mask:0xc
	v_mov_b32_dpp v13, v9 row_ror:8 row_mask:0xf bank_mask:0xc
	v_mov_b32_dpp v14, v10 row_ror:8 row_mask:0xf bank_mask:0xc
	v_mov_b32_dpp v15, v11 row_ror:8 row_mask:0xf bank_mask:0xc
	v_mov_b32_dpp v8, v190 row_ror:8 row_mask:0xf bank_mask:0x3
	v_mov_b32_dpp v9, v191 row_ror:8 row_mask:0xf bank_mask:0x3
	v_mov_b32_dpp v10, v192 row_ror:8 row_mask:0xf bank_mask:0x3
	v_mov_b32_dpp v11, v193 row_ror:8 row_mask:0xf bank_mask:0x3
	s_waitcnt vmcnt(18)
;     __device__ __forceinline__ void fused(f32x4 (&acc)[2][2][4][2], const Unit& u, int wr, int wc, int fr, int fq, PG8_LAS unsigned char* lds, int wid, int lane) const {
;     ...
; #pragma unroll
;         for (int ai = 0; ai < 2; ++ai)
; #pragma unroll
;             for (int m = 0; m < 4; ++m) { const int r = ai * HALF + wr * 64 + m * 16 + fr; const float rs = S[r]; const size_t off = (size_t)(row_off + u.pm * BM + r) * DM + col0;
; #pragma unroll
;                 for (int bj = 0; bj < 2; ++bj)
; #pragma unroll
;                     for (int n = 0; n < 2; ++n) { const f32x4 bs = *(const f32x4*)(base + off + bj * HALF + n * 16); __builtin_nontemporal_store(bs + acc[ai][bj][m][n] * rs * g[bj][n], (f32x4*)(out + off + bj * HALF + n * 16)); }
;                 if (m & 1) asm volatile("" ::: "memory"); }
;         asm volatile("s_waitcnt lgkmcnt(0)" ::: "memory"); __builtin_amdgcn_s_barrier(); asm volatile("" ::: "memory");
	v_mul_f32_e32 v12, v12, v240
	v_mul_f32_e32 v13, v13, v240
	v_mul_f32_e32 v14, v14, v240
	v_mul_f32_e32 v15, v15, v240
	v_mul_f32_e32 v8, v8, v241
	v_mul_f32_e32 v9, v9, v241
	v_mul_f32_e32 v10, v10, v241
	v_mul_f32_e32 v11, v11, v241
	v_fma_f32 v12, v12, v248, v204
	v_fma_f32 v13, v13, v249, v205
	v_fma_f32 v14, v14, v250, v206
	v_fma_f32 v15, v15, v251, v207
	v_fma_f32 v8, v8, v248, v208
	v_fma_f32 v9, v9, v249, v209
	v_fma_f32 v10, v10, v250, v210
	v_fma_f32 v11, v11, v251, v211
	v_add_u32_e32 v252, 0xa0000, v157
	v_add_u32_e32 v253, 0xa8000, v157
	global_store_dwordx4 v252, v[12:15], s[6:7] offset:512 nt
	global_store_dwordx4 v253, v[8:11], s[6:7] offset:512 nt
	v_mov_b32_e32 v190, v20
	v_mov_b32_e32 v191, v21
	v_mov_b32_e32 v192, v22
	v_mov_b32_e32 v193, v23
	v_mov_b32_dpp v20, v16 row_ror:8 row_mask:0xf bank_mask:0xc
	v_mov_b32_dpp v21, v17 row_ror:8 row_mask:0xf bank_mask:0xc
	v_mov_b32_dpp v22, v18 row_ror:8 row_mask:0xf bank_mask:0xc
	v_mov_b32_dpp v23, v19 row_ror:8 row_mask:0xf bank_mask:0xc
	v_mov_b32_dpp v16, v190 row_ror:8 row_mask:0xf bank_mask:0x3
	v_mov_b32_dpp v17, v191 row_ror:8 row_mask:0xf bank_mask:0x3
	v_mov_b32_dpp v18, v192 row_ror:8 row_mask:0xf bank_mask:0x3
	v_mov_b32_dpp v19, v193 row_ror:8 row_mask:0xf bank_mask:0x3
	s_waitcnt vmcnt(16)
	v_mul_f32_e32 v20, v20, v242
	v_mul_f32_e32 v21, v21, v242
	v_mul_f32_e32 v22, v22, v242
	v_mul_f32_e32 v23, v23, v242
	v_mul_f32_e32 v16, v16, v243
	v_mul_f32_e32 v17, v17, v243
	v_mul_f32_e32 v18, v18, v243
	v_mul_f32_e32 v19, v19, v243
	v_fma_f32 v20, v20, v244, v212
	v_fma_f32 v21, v21, v245, v213
	v_fma_f32 v22, v22, v246, v214
	v_fma_f32 v23, v23, v247, v215
	v_fma_f32 v16, v16, v244, v216
	v_fma_f32 v17, v17, v245, v217
	v_fma_f32 v18, v18, v246, v218
	v_fma_f32 v19, v19, v247, v219
	v_add_u32_e32 v252, 0xb0000, v157
	v_add_u32_e32 v253, 0xb8000, v157
	global_store_dwordx4 v252, v[20:23], s[6:7] nt
	global_store_dwordx4 v253, v[16:19], s[6:7] nt
	v_mov_b32_e32 v190, v4
	v_mov_b32_e32 v191, v5
	v_mov_b32_e32 v192, v6
	v_mov_b32_e32 v193, v7
	v_mov_b32_dpp v4, v0 row_ror:8 row_mask:0xf bank_mask:0xc
	v_mov_b32_dpp v5, v1 row_ror:8 row_mask:0xf bank_mask:0xc
	v_mov_b32_dpp v6, v2 row_ror:8 row_mask:0xf bank_mask:0xc
	v_mov_b32_dpp v7, v3 row_ror:8 row_mask:0xf bank_mask:0xc
	v_mov_b32_dpp v0, v190 row_ror:8 row_mask:0xf bank_mask:0x3
	v_mov_b32_dpp v1, v191 row_ror:8 row_mask:0xf bank_mask:0x3
	v_mov_b32_dpp v2, v192 row_ror:8 row_mask:0xf bank_mask:0x3
	v_mov_b32_dpp v3, v193 row_ror:8 row_mask:0xf bank_mask:0x3
	s_waitcnt vmcnt(14)
	v_mul_f32_e32 v4, v4, v242
	v_mul_f32_e32 v5, v5, v242
	v_mul_f32_e32 v6, v6, v242
	v_mul_f32_e32 v7, v7, v242
	v_mul_f32_e32 v0, v0, v243
	v_mul_f32_e32 v1, v1, v243
	v_mul_f32_e32 v2, v2, v243
	v_mul_f32_e32 v3, v3, v243
	v_fma_f32 v4, v4, v248, v220
	v_fma_f32 v5, v5, v249, v221
	v_fma_f32 v6, v6, v250, v222
	v_fma_f32 v7, v7, v251, v223
	v_fma_f32 v0, v0, v248, v224
	v_fma_f32 v1, v1, v249, v225
	v_fma_f32 v2, v2, v250, v226
	v_fma_f32 v3, v3, v251, v227
	v_add_u32_e32 v252, 0xb0000, v157
	v_add_u32_e32 v253, 0xb8000, v157
	global_store_dwordx4 v252, v[4:7], s[6:7] offset:512 nt
	global_store_dwordx4 v253, v[0:3], s[6:7] offset:512 nt
	s_waitcnt lgkmcnt(0)
	s_barrier

;     __device__ __forceinline__ void run(const f32x4 (&v)[2][2][4][2], const Unit& u, int wr, int wc, int fr, int fq, PG8_LAS unsigned char* lds, int wid, int lane) const {
;     ...
;             __hip_atomic_store(xbuf + ((size_t)(pmg * BM + row) * 4 + u.pn), tot, __ATOMIC_RELAXED, __HIP_MEMORY_SCOPE_AGENT);
;         }
;         asm volatile("s_waitcnt vmcnt(0)" ::: "memory");
;         if (lane == 0) __hip_atomic_fetch_add(cnt + 64 * pmg, 1u, __ATOMIC_RELAXED, __HIP_MEMORY_SCOPE_AGENT);
;         if (wid == 0) {
;             unsigned sp = 0;
;             while ((unsigned)__builtin_amdgcn_readfirstlane(__hip_atomic_load(cnt + 64 * pmg, __ATOMIC_RELAXED, __HIP_MEMORY_SCOPE_AGENT)) < 32u) { __builtin_amdgcn_s_sleep(2); if (++sp > (1u << 22)) break; }
;     __device__ __forceinline__ void fused(f32x4 (&acc)[2][2][4][2], const Unit& u, int wr, int wc, int fr, int fq, PG8_LAS unsigned char* lds, int wid, int lane) const {
;     ...
;         for (int bj = 0; bj < 2; ++bj)
; #pragma unroll
;             for (int n = 0; n < 2; ++n) g[bj][n] = *(const f32x4*)(gv + col0 + bj * HALF + n * 16);
; #pragma unroll
;         for (int ai = 0; ai < 2; ++ai)
; #pragma unroll
;             for (int m = 0; m < 4; ++m) { const int r = ai * HALF + wr * 64 + m * 16 + fr; const float rs = S[r]; const size_t off = (size_t)(row_off + u.pm * BM + r) * DM + col0;
; #pragma unroll
;                 for (int bj = 0; bj < 2; ++bj)
; #pragma unroll
;                     for (int n = 0; n < 2; ++n) { const f32x4 bs = *(const f32x4*)(base + off + bj * HALF + n * 16); __builtin_nontemporal_store(bs + acc[ai][bj][m][n] * rs * g[bj][n], (f32x4*)(out + off + bj * HALF + n * 16)); }
.LBB0_1160:
	s_or_b64 exec, exec, s[10:11]
	s_lshl_b32 s78, s50, 14
	s_lshl_b32 s76, s53, 8
	s_add_i32 s76, s76, s78
	s_mov_b32 s77, 0
	s_lshl_b64 s[76:77], s[76:77], 12
	s_add_u32 s76, s12, s76
	s_addc_u32 s77, s13, s77
	s_lshl_b32 s78, s16, 5
	s_lshl_b32 s79, s24, 8
	s_or_b32 s78, s79, s78
	v_lshrrev_b32_e32 v245, 2, v138
	v_and_or_b32 v245, v245, 12, s78
	v_lshlrev_b32_e32 v245, 2, v245
	v_and_b32_e32 v246, 8, v157
	v_sub_u32_e32 v244, v157, v246
	v_lshlrev_b32_e32 v246, 3, v246
	v_lshl_add_u32 v244, v244, 12, v245
	v_add_u32_e32 v244, v244, v246
	v_mov_b32_e32 v248, v244
	v_add_u32_e32 v249, 0x8000, v244
	global_load_dwordx4 v[158:161], v248, s[76:77] nt
	global_load_dwordx4 v[162:165], v249, s[76:77] nt
	v_mov_b32_e32 v248, v244
	v_add_u32_e32 v249, 0x8000, v244
	global_load_dwordx4 v[166:169], v248, s[76:77] offset:512 nt
	global_load_dwordx4 v[170:173], v249, s[76:77] offset:512 nt
	v_add_u32_e32 v248, 0x10000, v244
	v_add_u32_e32 v249, 0x18000, v244
	global_load_dwordx4 v[174:177], v248, s[76:77] nt
	global_load_dwordx4 v[178:181], v249, s[76:77] nt
	v_add_u32_e32 v248, 0x10000, v244
	v_add_u32_e32 v249, 0x18000, v244
	global_load_dwordx4 v[182:185], v248, s[76:77] offset:512 nt
	global_load_dwordx4 v[186:189], v249, s[76:77] offset:512 nt
	v_add_u32_e32 v248, 0x20000, v244
	v_add_u32_e32 v249, 0x28000, v244
	global_load_dwordx4 v[196:199], v248, s[76:77] nt
	global_load_dwordx4 v[200:203], v249, s[76:77] nt
	v_add_u32_e32 v248, 0x20000, v244
	v_add_u32_e32 v249, 0x28000, v244
	global_load_dwordx4 v[204:207], v248, s[76:77] offset:512 nt
	global_load_dwordx4 v[208:211], v249, s[76:77] offset:512 nt
	v_add_u32_e32 v248, 0x30000, v244
	v_add_u32_e32 v249, 0x38000, v244
	global_load_dwordx4 v[212:215], v248, s[76:77] nt
	global_load_dwordx4 v[216:219], v249, s[76:77] nt
	v_add_u32_e32 v248, 0x30000, v244
	v_add_u32_e32 v249, 0x38000, v244
	global_load_dwordx4 v[220:223], v248, s[76:77] offset:512 nt
	global_load_dwordx4 v[224:227], v249, s[76:77] offset:512 nt
	s_lshl_b32 s78, s50, 12
	s_add_i32 s78, s51, s78
	s_ashr_i32 s79, s78, 31
	s_lshl_b64 s[78:79], s[78:79], 2
	s_add_u32 s78, s14, s78
	s_addc_u32 s79, s15, s79
	s_add_u32 s78, s78, s22
	s_addc_u32 s79, s79, s23
	v_add_u32_e32 v250, v245, v246
	global_load_dwordx4 v[244:247], v250, s[78:79]
	global_load_dwordx4 v[248:251], v250, s[78:79] offset:512
	s_cmp_gt_u32 s52, 63
	s_cbranch_scc1 .LBB0_1170
	s_lshl_b32 s10, s28, 6
	s_ashr_i32 s11, s10, 31
	s_lshl_b64 s[10:11], s[10:11], 2
	s_add_u32 s10, s25, s10
	s_addc_u32 s11, s29, s11
	s_mov_b32 s25, 0x400001
	s_branch .LBB0_1163

;     __device__ __forceinline__ void run(const f32x4 (&v)[2][2][4][2], const Unit& u, int wr, int wc, int fr, int fq, PG8_LAS unsigned char* lds, int wid, int lane) const {
;     ...
;         asm volatile("s_waitcnt vmcnt(0) lgkmcnt(0)" ::: "memory"); __builtin_amdgcn_s_barrier(); asm volatile("" ::: "memory");
;         if (lane < 32) {
;             const float* slot = xbuf + (size_t)(pmg * BM + row) * 4; float t = 0.f;
; #pragma unroll
;             for (int k = 0; k < 4; ++k) t += __hip_atomic_load(slot + k, __ATOMIC_RELAXED, __HIP_MEMORY_SCOPE_AGENT);
;             S[row] = rsqrtf(t * (1.0f / 1024.0f) + eps);
;         }
.LBB0_1169:
.LBB0_1170:
	s_waitcnt vmcnt(18) lgkmcnt(0)
	s_barrier
	s_and_saveexec_b64 s[10:11], s[6:7]
	s_cbranch_execz .LBB0_1113
	s_waitcnt lgkmcnt(0)
	v_ashrrev_i32_e32 v129, 31, v128
	v_lshl_add_u64 v[128:129], v[128:129], 4, s[8:9]
	global_load_dword v130, v[128:129], off sc1
	global_load_dword v132, v[128:129], off offset:4 sc1
	global_load_dword v133, v[128:129], off offset:8 sc1
	s_nop 0
	global_load_dword v128, v[128:129], off offset:12 sc1
	s_waitcnt vmcnt(0)
	v_add_f32_e32 v129, 0, v130
	v_add_f32_e32 v129, v129, v132
	v_add_f32_e32 v129, v129, v133
	v_add_f32_e32 v128, v129, v128
	v_fmamk_f32 v128, v128, 0x3a800000, v154
	v_mul_f32_e32 v129, 0x4b800000, v128
	v_cmp_gt_f32_e32 vcc, s48, v128
	s_nop 1
	v_cndmask_b32_e32 v128, v128, v129, vcc
	v_rsq_f32_e32 v128, v128
	s_nop 0
	v_mul_f32_e32 v129, 0x45800000, v128
	v_cndmask_b32_e32 v128, v128, v129, vcc
	v_lshl_add_u32 v129, v131, 2, 0
	ds_write_b32 v129, v128 offset:4096
	s_branch .LBB0_1113
